# plus attention: row-max temporaries renamed off MFMA result registers (s_nop 5 x4 removed), K-slot address arithmetic issued in front of the tile barrier
# baseline (speedup 1.0000x reference)
.LBB0_961:
	s_mov_b32 s19, s5
	s_mov_b32 s5, s25
	s_mul_i32 s9, s25, 0x6000
	s_add_i32 s25, s9, 0
	v_add_u32_e32 v124, s25, v225
	s_waitcnt vmcnt(5)
	s_barrier
	ds_read_b128 v[120:123], v124
	ds_read_b128 v[160:163], v124 offset:4096
	ds_read_b128 v[168:171], v124 offset:8192
	ds_read_b128 v[172:175], v124 offset:12288
	v_exp_f32_e32 v188, v148
	v_exp_f32_e32 v189, v149
	v_exp_f32_e32 v194, v150
	v_exp_f32_e32 v195, v151
	s_waitcnt lgkmcnt(3)
	v_mfma_f32_16x16x32_bf16 v[124:127], v[120:123], v[4:7], v[48:51]
	v_mfma_f32_16x16x32_bf16 v[120:123], v[120:123], v[40:43], v[52:55]
	v_add_u32_e32 v196, s25, v234
	ds_read_b128 v[184:187], v196
	s_waitcnt lgkmcnt(3)
	v_mfma_f32_16x16x32_bf16 v[148:151], v[160:163], v[4:7], v[48:51]
	v_add_f32_e32 v180, v157, v156
	v_add_f32_e32 v181, v145, v144
	v_mfma_f32_16x16x32_bf16 v[160:163], v[160:163], v[40:43], v[52:55]
	ds_read_b128 v[176:179], v196 offset:4096
	s_waitcnt lgkmcnt(3)
	v_mfma_f32_16x16x32_bf16 v[164:167], v[168:171], v[4:7], v[48:51]
	v_exp_f32_e32 v190, v140
	v_exp_f32_e32 v191, v141
	v_add_f32_e32 v206, v158, v180
	v_mfma_f32_16x16x32_bf16 v[168:171], v[168:171], v[40:43], v[52:55]
	v_add_f32_e32 v207, v146, v181
	ds_read_b128 v[180:183], v196 offset:8192
	v_exp_f32_e32 v192, v142
	v_exp_f32_e32 v193, v143
	s_waitcnt lgkmcnt(3)
	v_mfma_f32_16x16x32_bf16 v[140:143], v[172:175], v[4:7], v[48:51]
	v_add_f32_e32 v206, v159, v206
	v_add_f32_e32 v207, v147, v207
	v_mfma_f32_16x16x32_bf16 v[172:175], v[172:175], v[40:43], v[52:55]
	s_add_i32 s9, s4, -1
	s_cmp_ge_u32 s9, s2
	s_cbranch_scc1 .LBB0_963
	s_add_u32 s9, s6, s30
	s_addc_u32 s35, s7, s31
	s_add_u32 s34, s9, 0x180000
	s_addc_u32 s35, s35, 0
	s_add_u32 s36, s10, 0xffffe000
	s_mul_i32 s9, s8, 0x6000
	s_addc_u32 s37, s11, -1
	s_add_i32 s9, s9, 0
	s_add_i32 s48, s9, s77
	s_mov_b32 m0, s48
	s_add_i32 s9, s9, s97
	global_load_lds_dwordx4 v227, s[34:35]
	s_add_i32 m0, s48, 0x400
	s_nop 0
	global_load_lds_dwordx4 v229, s[34:35]
	s_add_i32 m0, s9, 0x4000
	s_nop 0
	global_load_lds_dwordx4 v232, s[36:37]
.LBB0_963:
	s_add_u32 s36, s28, s30
	s_addc_u32 s37, s29, s31
	s_add_u32 s34, s36, 0x100000
	s_addc_u32 s35, s37, 0
	s_lshl_b32 s9, s19, 14
	s_add_i32 s48, s95, s9
	s_mov_b32 m0, s48
	s_nop 0
	global_load_lds_dwordx4 v228, s[34:35]
	s_add_i32 m0, s48, 0x400
	s_nop 0
	global_load_lds_dwordx4 v231, s[34:35]
	ds_read_b128 v[236:239], v196 offset:12288
	s_waitcnt lgkmcnt(3)
	v_mfma_f32_16x16x32_bf16 v[120:123], v[184:187], v[36:39], v[120:123]
	v_exp_f32_e32 v196, v132
	v_exp_f32_e32 v208, v133
	v_add_f32_e32 v206, v152, v206
	v_add_f32_e32 v207, v136, v207
	v_mfma_f32_16x16x32_bf16 v[124:127], v[184:187], v[0:3], v[124:127]
	v_add_u32_e32 v209, s25, v233
	ds_read_b128 v[184:187], v209
	v_exp_f32_e32 v210, v134
	v_exp_f32_e32 v211, v135
	s_waitcnt lgkmcnt(3)
	v_mfma_f32_16x16x32_bf16 v[132:135], v[176:179], v[0:3], v[148:151]
	v_mfma_f32_16x16x32_bf16 v[160:163], v[176:179], v[36:39], v[160:163]
	s_nop 1
	v_add_f32_e32 v148, v153, v206
	v_add_f32_e32 v149, v137, v207
	ds_read_b128 v[176:179], v209 offset:4096
	s_waitcnt lgkmcnt(3)
	v_mfma_f32_16x16x32_bf16 v[164:167], v[180:183], v[0:3], v[164:167]
	v_exp_f32_e32 v212, v128
	v_exp_f32_e32 v213, v129
	v_add_f32_e32 v148, v154, v148
	v_mfma_f32_16x16x32_bf16 v[168:171], v[180:183], v[36:39], v[168:171]
	v_add_f32_e32 v149, v138, v149
	ds_read_b128 v[180:183], v209 offset:8192
	v_exp_f32_e32 v219, v130
	v_exp_f32_e32 v235, v131
	s_waitcnt lgkmcnt(3)
	v_mfma_f32_16x16x32_bf16 v[128:131], v[236:239], v[0:3], v[140:143]
	v_add_f32_e32 v148, v155, v148
	v_add_f32_e32 v149, v139, v149
	v_mfma_f32_16x16x32_bf16 v[140:143], v[236:239], v[36:39], v[172:175]
	s_nop 2
	ds_read_b128 v[172:175], v209 offset:12288
	s_waitcnt lgkmcnt(3)
	v_mfma_f32_16x16x32_bf16 v[120:123], v[184:187], v[28:31], v[120:123]
	v_add_f32_e32 v150, v188, v148
	v_add_f32_e32 v149, v190, v149
	v_mfma_f32_16x16x32_bf16 v[124:127], v[184:187], v[12:15], v[124:127]
	v_cvt_pk_bf16_f32 v148, v156, v157
	v_add_u32_e32 v206, s25, v230
	ds_read_b128 v[184:187], v206
	v_add_f32_e32 v150, v189, v150
	v_add_f32_e32 v151, v191, v149
	s_waitcnt lgkmcnt(3)
	v_mfma_f32_16x16x32_bf16 v[132:135], v[176:179], v[12:15], v[132:135]
	v_cvt_pk_bf16_f32 v149, v158, v159
	v_mfma_f32_16x16x32_bf16 v[156:159], v[176:179], v[28:31], v[160:163]
	ds_read_b128 v[176:179], v206 offset:4096
	s_waitcnt lgkmcnt(3)
	v_mfma_f32_16x16x32_bf16 v[162:165], v[180:183], v[12:15], v[164:167]
	s_nop 0
	v_add_f32_e32 v160, v194, v150
	v_add_f32_e32 v151, v192, v151
	v_mfma_f32_16x16x32_bf16 v[166:169], v[180:183], v[28:31], v[168:171]
	v_cvt_pk_bf16_f32 v150, v152, v153
	ds_read_b128 v[180:183], v206 offset:8192
	s_waitcnt lgkmcnt(3)
	v_mfma_f32_16x16x32_bf16 v[128:131], v[172:175], v[12:15], v[128:131]
	v_add_f32_e32 v160, v195, v160
	v_add_f32_e32 v161, v193, v151
	v_mfma_f32_16x16x32_bf16 v[140:143], v[172:175], v[28:31], v[140:143]
	v_cvt_pk_bf16_f32 v151, v154, v155
	ds_read_b128 v[152:155], v206 offset:12288
	s_waitcnt lgkmcnt(3)
	v_mfma_f32_16x16x32_bf16 v[120:123], v[184:187], v[24:27], v[120:123]
	v_add_f32_e32 v174, v196, v160
	v_add_f32_e32 v161, v212, v161
	v_mfma_f32_16x16x32_bf16 v[124:127], v[184:187], v[8:11], v[124:127]
	v_cvt_pk_bf16_f32 v160, v144, v145
	v_add_u32_e32 v186, s25, v226
	ds_read_b128 v[170:173], v186 offset:16384
	v_add_f32_e32 v184, v208, v174
	v_add_f32_e32 v185, v213, v161
	s_waitcnt lgkmcnt(3)
	v_mfma_f32_16x16x32_bf16 v[132:135], v[176:179], v[8:11], v[132:135]
	v_cvt_pk_bf16_f32 v161, v146, v147
	v_mfma_f32_16x16x32_bf16 v[144:147], v[176:179], v[24:27], v[156:159]
	s_nop 2
	ds_read_b128 v[156:159], v186 offset:18432
	s_waitcnt lgkmcnt(3)
	v_mfma_f32_16x16x32_bf16 v[174:177], v[180:183], v[8:11], v[162:165]
	v_mfma_f32_16x16x32_bf16 v[178:181], v[180:183], v[24:27], v[166:169]
	s_nop 1
	v_add_f32_e32 v163, v210, v184
	v_add_f32_e32 v164, v219, v185
	v_cvt_pk_bf16_f32 v162, v136, v137
	ds_read_b128 v[182:185], v186 offset:20480
	v_add_f32_e32 v206, v211, v163
	v_add_f32_e32 v207, v235, v164
	s_waitcnt lgkmcnt(3)
	v_mfma_f32_16x16x32_bf16 v[128:131], v[152:155], v[8:11], v[128:131]
	v_cvt_pk_bf16_f32 v163, v138, v139
	v_mfma_f32_16x16x32_bf16 v[136:139], v[152:155], v[24:27], v[140:143]
	s_nop 2
	ds_read_b128 v[140:143], v186 offset:22528
	s_waitcnt lgkmcnt(3)
	v_mfma_f32_16x16x32_bf16 v[120:123], v[170:173], v[32:35], v[120:123]
	v_cvt_pk_bf16_f32 v164, v188, v189
	v_mfma_f32_16x16x32_bf16 v[124:127], v[170:173], v[16:19], v[124:127]
	v_add_u32_e32 v152, s25, v224
	ds_read_b128 v[168:171], v152 offset:16384
	s_waitcnt lgkmcnt(3)
	v_mfma_f32_16x16x32_bf16 v[132:135], v[156:159], v[16:19], v[132:135]
	v_cvt_pk_bf16_f32 v165, v194, v195
	v_mfma_f32_16x16x32_bf16 v[186:189], v[156:159], v[32:35], v[144:147]
	ds_read_b128 v[236:239], v152 offset:18432
	s_waitcnt lgkmcnt(3)
	v_mfma_f32_16x16x32_bf16 v[240:243], v[182:185], v[16:19], v[174:177]
	v_cvt_pk_bf16_f32 v166, v196, v208
	v_mfma_f32_16x16x32_bf16 v[176:179], v[182:185], v[32:35], v[178:181]
	s_nop 2
	ds_read_b128 v[180:183], v152 offset:20480
	s_waitcnt lgkmcnt(3)
	v_mfma_f32_16x16x32_bf16 v[128:131], v[140:143], v[16:19], v[128:131]
	v_cvt_pk_bf16_f32 v167, v210, v211
	v_mfma_f32_16x16x32_bf16 v[244:247], v[140:143], v[32:35], v[136:139]
	ds_read_b128 v[248:251], v152 offset:22528
	s_waitcnt lgkmcnt(3)
	v_mfma_f32_16x16x32_bf16 v[152:155], v[168:171], v[20:23], v[124:127]
	v_mfma_f32_16x16x32_bf16 v[144:147], v[168:171], v[44:47], v[120:123]
	v_cvt_pk_bf16_f32 v168, v190, v191
	s_waitcnt lgkmcnt(2)
	v_mfma_f32_16x16x32_bf16 v[156:159], v[236:239], v[20:23], v[132:135]
	v_cvt_pk_bf16_f32 v169, v192, v193
	v_mfma_f32_16x16x32_bf16 v[172:175], v[236:239], v[44:47], v[186:189]
	s_waitcnt lgkmcnt(1)
	v_mfma_f32_16x16x32_bf16 v[140:143], v[180:183], v[20:23], v[240:243]
	v_cvt_pk_bf16_f32 v170, v212, v213
	v_mfma_f32_16x16x32_bf16 v[136:139], v[180:183], v[44:47], v[176:179]
	s_waitcnt lgkmcnt(0)
	v_mfma_f32_16x16x32_bf16 v[132:135], v[248:251], v[20:23], v[128:131]
	v_cvt_pk_bf16_f32 v171, v219, v235
	v_mfma_f32_16x16x32_bf16 v[128:131], v[248:251], v[44:47], v[244:247]
	s_lshl_b32 s34, s8, 14
	s_add_i32 s48, s34, 0
	s_add_i32 s48, s48, 0x12000
	v_add_u32_e32 v196, s48, v222
	v_add_u32_e32 v219, s48, v223
	ds_read_b64_tr_b16 v[176:177], v219
	ds_read_b64_tr_b16 v[178:179], v219 offset:4096
	ds_read_b64_tr_b16 v[184:185], v219 offset:8192
	ds_read_b64_tr_b16 v[186:187], v219 offset:12288
	ds_read_b64_tr_b16 v[120:121], v196
	ds_read_b64_tr_b16 v[122:123], v196 offset:4096
	ds_read_b64_tr_b16 v[124:125], v196 offset:8192
	ds_read_b64_tr_b16 v[126:127], v196 offset:12288
	ds_read_b64_tr_b16 v[182:183], v219 offset:4608
	ds_read_b64_tr_b16 v[180:181], v219 offset:512
	ds_read_b64_tr_b16 v[190:191], v219 offset:12800
	ds_read_b64_tr_b16 v[188:189], v219 offset:8704
	s_waitcnt lgkmcnt(10)
	v_mfma_f32_16x16x32_bf16 v[112:115], v[176:179], v[148:151], v[112:115]
	v_mfma_f32_16x16x32_bf16 v[116:119], v[176:179], v[160:163], v[116:119]
	v_max_f32_e32 v176, v152, v153
	s_waitcnt lgkmcnt(8)
	v_mfma_f32_16x16x32_bf16 v[112:115], v[184:187], v[164:167], v[112:115]
	v_max3_f32 v176, v176, v154, v155
	v_max3_f32 v176, v176, v156, v157
	v_max3_f32 v208, v176, v158, v159
	v_mfma_f32_16x16x32_bf16 v[116:119], v[184:187], v[168:171], v[116:119]
	ds_read_b64_tr_b16 v[192:193], v196 offset:512
	ds_read_b64_tr_b16 v[194:195], v196 offset:4608
	ds_read_b64_tr_b16 v[236:237], v196 offset:8704
	ds_read_b64_tr_b16 v[238:239], v196 offset:12800
	s_waitcnt lgkmcnt(10)
	v_mfma_f32_16x16x32_bf16 v[108:111], v[120:123], v[148:151], v[108:111]
	v_mfma_f32_16x16x32_bf16 v[176:179], v[120:123], v[160:163], v[104:107]
	s_waitcnt lgkmcnt(8)
	v_mfma_f32_16x16x32_bf16 v[104:107], v[124:127], v[164:167], v[108:111]
	v_max3_f32 v252, v208, v140, v141
	v_max3_f32 v252, v252, v142, v143
	v_max3_f32 v252, v252, v132, v133
	v_max3_f32 v120, v252, v134, v135
	v_mfma_f32_16x16x32_bf16 v[108:111], v[124:127], v[168:171], v[176:179]
	ds_read_b64_tr_b16 v[184:185], v219 offset:1024
	ds_read_b64_tr_b16 v[186:187], v219 offset:5120
	s_nop 0
	ds_read_b64_tr_b16 v[176:177], v219 offset:9216
	ds_read_b64_tr_b16 v[178:179], v219 offset:13312
	s_waitcnt lgkmcnt(10)
	v_mfma_f32_16x16x32_bf16 v[96:99], v[180:183], v[148:151], v[96:99]
	v_max_f32_e32 v121, v144, v145
	s_waitcnt lgkmcnt(8)
	v_mfma_f32_16x16x32_bf16 v[96:99], v[188:191], v[164:167], v[96:99]
	v_max3_f32 v121, v121, v146, v147
	v_max3_f32 v121, v121, v172, v173
	v_max3_f32 v121, v121, v174, v175
	v_mfma_f32_16x16x32_bf16 v[100:103], v[180:183], v[160:163], v[100:103]
	v_mfma_f32_16x16x32_bf16 v[100:103], v[188:191], v[168:171], v[100:103]
	ds_read_b64_tr_b16 v[188:189], v196 offset:1024
	ds_read_b64_tr_b16 v[190:191], v196 offset:5120
	ds_read_b64_tr_b16 v[180:181], v196 offset:9216
	ds_read_b64_tr_b16 v[182:183], v196 offset:13312
	s_waitcnt lgkmcnt(10)
	v_mfma_f32_16x16x32_bf16 v[92:95], v[192:195], v[148:151], v[92:95]
	v_mfma_f32_16x16x32_bf16 v[122:125], v[192:195], v[160:163], v[88:91]
	s_waitcnt lgkmcnt(8)
	v_mfma_f32_16x16x32_bf16 v[88:91], v[236:239], v[164:167], v[92:95]
	v_max3_f32 v252, v121, v136, v137
	v_max3_f32 v252, v252, v138, v139
	v_max3_f32 v252, v252, v128, v129
	v_max3_f32 v121, v252, v130, v131
	v_mfma_f32_16x16x32_bf16 v[92:95], v[236:239], v[168:171], v[122:125]
	s_nop 2
	v_max_f32_e32 v122, v120, v121
	v_cmp_ge_f32_e32 vcc, s62, v122
	s_cmp_lg_u64 vcc, exec
	s_cselect_b64 s[34:35], -1, 0
	s_cmp_eq_u64 vcc, exec
	s_cbranch_scc1 .LBB0_965
	ds_bpermute_b32 v48, v220, v120
	v_max_f32_e32 v49, v120, v120
	v_max_f32_e32 v50, v121, v121
	s_waitcnt lgkmcnt(0)
	v_max_f32_e32 v48, v48, v48
	v_max_f32_e32 v48, v49, v48
	ds_bpermute_b32 v49, v221, v48
	s_waitcnt lgkmcnt(0)
	v_max3_f32 v48, v48, v49, 0
	ds_bpermute_b32 v49, v220, v121
	v_exp_f32_e64 v208, -v48
	v_sub_f32_e32 v152, v152, v48
	v_sub_f32_e32 v153, v153, v48
	v_sub_f32_e32 v154, v154, v48
	s_waitcnt lgkmcnt(0)
	v_max_f32_e32 v49, v49, v49
	v_max_f32_e32 v49, v50, v49
	ds_bpermute_b32 v50, v221, v49
	v_sub_f32_e32 v155, v155, v48
	v_sub_f32_e32 v156, v156, v48
	v_sub_f32_e32 v157, v157, v48
	v_sub_f32_e32 v158, v158, v48
	s_waitcnt lgkmcnt(0)
	v_max3_f32 v49, v49, v50, 0
	v_exp_f32_e64 v209, -v49
	v_pk_add_f32 v[202:203], v[202:203], v[48:49]
	v_sub_f32_e32 v159, v159, v48
	v_pk_add_f32 v[120:121], v[202:203], 0 neg_lo:[1,1] neg_hi:[1,1]
	v_xor_b32_e32 v124, 0x80000000, v203
	v_sub_f32_e32 v143, v143, v48
	v_sub_f32_e32 v142, v142, v48
	v_sub_f32_e32 v141, v141, v48
	v_sub_f32_e32 v140, v140, v48
	v_sub_f32_e32 v135, v135, v48
	v_sub_f32_e32 v134, v134, v48
	v_sub_f32_e32 v133, v133, v48
	v_sub_f32_e32 v132, v132, v48
	v_mov_b32_e32 v121, v120
	v_mov_b32_e32 v122, v120
	v_mov_b32_e32 v123, v120
	v_sub_f32_e32 v144, v144, v49
	v_sub_f32_e32 v145, v145, v49
	v_sub_f32_e32 v146, v146, v49
	v_sub_f32_e32 v147, v147, v49
	v_sub_f32_e32 v172, v172, v49
	v_sub_f32_e32 v173, v173, v49
	v_sub_f32_e32 v174, v174, v49
	v_sub_f32_e32 v175, v175, v49
	v_sub_f32_e32 v139, v139, v49
	v_sub_f32_e32 v138, v138, v49
	v_sub_f32_e32 v137, v137, v49
	v_sub_f32_e32 v136, v136, v49
	v_sub_f32_e32 v131, v131, v49
	v_sub_f32_e32 v130, v130, v49
	v_sub_f32_e32 v129, v129, v49
	v_sub_f32_e32 v128, v128, v49
	v_mov_b32_e32 v125, v124
	v_mov_b32_e32 v126, v124
	v_mov_b32_e32 v127, v124
	v_mov_b32_e32 v48, v120
	v_mov_b32_e32 v49, v120
	v_mov_b32_e32 v50, v120
	v_mov_b32_e32 v51, v120
	v_mov_b32_e32 v52, v124
	v_mov_b32_e32 v53, v124
	v_mov_b32_e32 v54, v124
	v_mov_b32_e32 v55, v124
	s_branch .LBB0_966

.LBB0_969:
	s_mul_i32 s34, s19, 0x6000
	s_add_i32 s49, s34, 0
	v_add_u32_e32 v164, s49, v225
	s_waitcnt vmcnt(5)
	s_barrier
	ds_read_b128 v[160:163], v164
	ds_read_b128 v[168:171], v164 offset:4096
	ds_read_b128 v[184:187], v164 offset:8192
	ds_read_b128 v[246:249], v164 offset:12288
	v_exp_f32_e32 v235, v140
	v_exp_f32_e32 v236, v141
	v_exp_f32_e32 v241, v142
	v_exp_f32_e32 v242, v143
	s_waitcnt lgkmcnt(3)
	v_mfma_f32_16x16x32_bf16 v[164:167], v[160:163], v[4:7], v[120:123]
	v_mfma_f32_16x16x32_bf16 v[160:163], v[160:163], v[40:43], v[124:127]
	v_add_u32_e32 v243, s49, v234
	ds_read_b128 v[192:195], v243
	s_waitcnt lgkmcnt(3)
	v_mfma_f32_16x16x32_bf16 v[180:183], v[168:171], v[4:7], v[120:123]
	v_add_f32_e32 v140, v153, v152
	v_mfma_f32_16x16x32_bf16 v[172:175], v[168:171], v[40:43], v[124:127]
	v_add_f32_e32 v141, v145, v144
	ds_read_b128 v[188:191], v243 offset:4096
	v_exp_f32_e32 v237, v136
	v_exp_f32_e32 v238, v137
	s_waitcnt lgkmcnt(3)
	v_mfma_f32_16x16x32_bf16 v[176:179], v[184:187], v[4:7], v[120:123]
	v_add_f32_e32 v136, v154, v140
	v_add_f32_e32 v137, v146, v141
	v_mfma_f32_16x16x32_bf16 v[140:143], v[184:187], v[40:43], v[124:127]
	ds_read_b128 v[184:187], v243 offset:8192
	v_exp_f32_e32 v239, v138
	v_exp_f32_e32 v240, v139
	s_waitcnt lgkmcnt(3)
	v_mfma_f32_16x16x32_bf16 v[168:171], v[246:249], v[4:7], v[120:123]
	v_add_f32_e32 v245, v155, v136
	v_add_f32_e32 v244, v147, v137
	v_mfma_f32_16x16x32_bf16 v[136:139], v[246:249], v[40:43], v[124:127]
	s_cmp_ge_u32 s4, s2
	s_cselect_b64 s[34:35], -1, 0
	s_and_b64 vcc, exec, s[34:35]
	s_cbranch_vccnz .LBB0_971
	s_add_u32 s65, s6, s30
	s_addc_u32 s69, s7, s31
	s_add_u32 s70, s65, 0x200000
	s_addc_u32 s71, s69, 0
	s_add_i32 s65, s25, s77
	s_mov_b64 s[80:81], s[10:11]
	s_mov_b32 m0, s65
	s_add_i32 s25, s25, s97
	global_load_lds_dwordx4 v227, s[70:71]
	s_add_i32 m0, s65, 0x400
	s_nop 0
	global_load_lds_dwordx4 v229, s[70:71]
	s_add_i32 m0, s25, 0x4000
	s_nop 0
	global_load_lds_dwordx4 v232, s[80:81]
.LBB0_971:
	s_add_u32 s36, s36, 0x180000
	s_addc_u32 s37, s37, 0
	s_add_i32 s25, s48, s77
	s_mov_b32 m0, s25
	s_nop 0
	global_load_lds_dwordx4 v228, s[36:37]
	s_add_i32 m0, s25, 0x400
	s_nop 0
	global_load_lds_dwordx4 v231, s[36:37]
	ds_read_b128 v[246:249], v243 offset:12288
	s_waitcnt lgkmcnt(3)
	v_mfma_f32_16x16x32_bf16 v[164:167], v[192:195], v[0:3], v[164:167]
	v_exp_f32_e32 v210, v132
	v_exp_f32_e32 v211, v133
	v_add_f32_e32 v212, v156, v245
	v_mfma_f32_16x16x32_bf16 v[160:163], v[192:195], v[36:39], v[160:163]
	v_add_f32_e32 v213, v148, v244
	v_add_u32_e32 v243, s49, v233
	ds_read_b128 v[192:195], v243
	v_exp_f32_e32 v250, v134
	v_exp_f32_e32 v251, v135
	s_waitcnt lgkmcnt(3)
	v_mfma_f32_16x16x32_bf16 v[132:135], v[188:191], v[0:3], v[180:183]
	v_add_f32_e32 v212, v157, v212
	v_add_f32_e32 v213, v149, v213
	v_mfma_f32_16x16x32_bf16 v[172:175], v[188:191], v[36:39], v[172:175]
	ds_read_b128 v[180:183], v243 offset:4096
	s_waitcnt lgkmcnt(3)
	v_mfma_f32_16x16x32_bf16 v[176:179], v[184:187], v[0:3], v[176:179]
	v_exp_f32_e32 v215, v128
	v_exp_f32_e32 v214, v129
	v_add_f32_e32 v188, v158, v212
	v_mfma_f32_16x16x32_bf16 v[140:143], v[184:187], v[36:39], v[140:143]
	v_add_f32_e32 v189, v150, v213
	ds_read_b128 v[184:187], v243 offset:8192
	v_exp_f32_e32 v218, v130
	v_exp_f32_e32 v198, v131
	s_waitcnt lgkmcnt(3)
	v_mfma_f32_16x16x32_bf16 v[128:131], v[246:249], v[0:3], v[168:171]
	v_add_f32_e32 v199, v159, v188
	v_add_f32_e32 v212, v151, v189
	v_mfma_f32_16x16x32_bf16 v[168:171], v[246:249], v[36:39], v[136:139]
	ds_read_b128 v[188:191], v243 offset:12288
	s_waitcnt lgkmcnt(3)
	v_mfma_f32_16x16x32_bf16 v[164:167], v[192:195], v[12:15], v[164:167]
	v_add_f32_e32 v137, v235, v199
	v_add_f32_e32 v138, v237, v212
	v_mfma_f32_16x16x32_bf16 v[160:163], v[192:195], v[28:31], v[160:163]
	v_cvt_pk_bf16_f32 v136, v152, v153
	v_add_u32_e32 v199, s49, v230
	ds_read_b128 v[192:195], v199
	v_add_f32_e32 v139, v236, v137
	v_add_f32_e32 v138, v238, v138
	s_waitcnt lgkmcnt(3)
	v_mfma_f32_16x16x32_bf16 v[132:135], v[180:183], v[12:15], v[132:135]
	v_cvt_pk_bf16_f32 v137, v154, v155
	v_mfma_f32_16x16x32_bf16 v[152:155], v[180:183], v[28:31], v[172:175]
	s_nop 2
	ds_read_b128 v[172:175], v199 offset:4096
	s_waitcnt lgkmcnt(3)
	v_mfma_f32_16x16x32_bf16 v[176:179], v[184:187], v[12:15], v[176:179]
	v_add_f32_e32 v139, v241, v139
	v_add_f32_e32 v212, v239, v138
	v_mfma_f32_16x16x32_bf16 v[140:143], v[184:187], v[28:31], v[140:143]
	v_cvt_pk_bf16_f32 v138, v156, v157
	ds_read_b128 v[180:183], v199 offset:8192
	v_add_f32_e32 v213, v242, v139
	v_add_f32_e32 v212, v240, v212
	s_waitcnt lgkmcnt(3)
	v_mfma_f32_16x16x32_bf16 v[128:131], v[188:191], v[12:15], v[128:131]
	v_cvt_pk_bf16_f32 v139, v158, v159
	v_mfma_f32_16x16x32_bf16 v[156:159], v[188:191], v[28:31], v[168:171]
	s_nop 2
	ds_read_b128 v[168:171], v199 offset:12288
	s_waitcnt lgkmcnt(3)
	v_mfma_f32_16x16x32_bf16 v[164:167], v[192:195], v[8:11], v[164:167]
	v_mfma_f32_16x16x32_bf16 v[184:187], v[192:195], v[24:27], v[160:163]
	s_nop 2
	v_add_f32_e32 v161, v210, v213
	v_add_f32_e32 v162, v215, v212
	v_cvt_pk_bf16_f32 v160, v144, v145
	v_add_u32_e32 v192, s49, v226
	ds_read_b128 v[188:191], v192 offset:16384
	v_add_f32_e32 v163, v211, v161
	v_add_f32_e32 v162, v214, v162
	s_waitcnt lgkmcnt(3)
	v_mfma_f32_16x16x32_bf16 v[132:135], v[172:175], v[8:11], v[132:135]
	v_cvt_pk_bf16_f32 v161, v146, v147
	v_mfma_f32_16x16x32_bf16 v[144:147], v[172:175], v[24:27], v[152:155]
	s_nop 2
	ds_read_b128 v[152:155], v192 offset:18432
	s_waitcnt lgkmcnt(3)
	v_mfma_f32_16x16x32_bf16 v[172:175], v[180:183], v[8:11], v[176:179]
	v_add_f32_e32 v163, v250, v163
	v_add_f32_e32 v193, v218, v162
	v_mfma_f32_16x16x32_bf16 v[140:143], v[180:183], v[24:27], v[140:143]
	v_cvt_pk_bf16_f32 v162, v148, v149
	ds_read_b128 v[176:179], v192 offset:20480
	v_add_f32_e32 v194, v251, v163
	v_add_f32_e32 v195, v198, v193
	s_waitcnt lgkmcnt(3)
	v_mfma_f32_16x16x32_bf16 v[128:131], v[168:171], v[8:11], v[128:131]
	v_cvt_pk_bf16_f32 v163, v150, v151
	v_mfma_f32_16x16x32_bf16 v[148:151], v[168:171], v[24:27], v[156:159]
	s_nop 2
	ds_read_b128 v[156:159], v192 offset:22528
	s_waitcnt lgkmcnt(3)
	v_mfma_f32_16x16x32_bf16 v[168:171], v[188:191], v[16:19], v[164:167]
	v_cvt_pk_bf16_f32 v164, v235, v236
	v_mfma_f32_16x16x32_bf16 v[180:183], v[188:191], v[32:35], v[184:187]
	v_add_u32_e32 v192, s49, v224
	s_nop 1
	ds_read_b128 v[184:187], v192 offset:16384
	s_waitcnt lgkmcnt(3)
	v_mfma_f32_16x16x32_bf16 v[132:135], v[152:155], v[16:19], v[132:135]
	v_cvt_pk_bf16_f32 v165, v241, v242
	v_mfma_f32_16x16x32_bf16 v[188:191], v[152:155], v[32:35], v[144:147]
	ds_read_b128 v[242:245], v192 offset:18432
	s_waitcnt lgkmcnt(3)
	v_mfma_f32_16x16x32_bf16 v[140:143], v[176:179], v[32:35], v[140:143]
	v_cvt_pk_bf16_f32 v166, v210, v211
	v_mfma_f32_16x16x32_bf16 v[246:249], v[176:179], v[16:19], v[172:175]
	ds_read_b128 v[176:179], v192 offset:20480
	s_waitcnt lgkmcnt(3)
	v_mfma_f32_16x16x32_bf16 v[128:131], v[156:159], v[16:19], v[128:131]
	v_cvt_pk_bf16_f32 v167, v250, v251
	v_mfma_f32_16x16x32_bf16 v[250:253], v[156:159], v[32:35], v[148:151]
	ds_read_b128 v[210:213], v192 offset:22528
	s_waitcnt lgkmcnt(3)
	v_mfma_f32_16x16x32_bf16 v[156:159], v[184:187], v[20:23], v[168:171]
	v_cvt_pk_bf16_f32 v168, v237, v238
	v_mfma_f32_16x16x32_bf16 v[144:147], v[184:187], v[44:47], v[180:183]
	s_waitcnt lgkmcnt(2)
	v_mfma_f32_16x16x32_bf16 v[152:155], v[242:245], v[20:23], v[132:135]
	v_cvt_pk_bf16_f32 v169, v239, v240
	v_mfma_f32_16x16x32_bf16 v[172:175], v[242:245], v[44:47], v[188:191]
	s_waitcnt lgkmcnt(1)
	v_mfma_f32_16x16x32_bf16 v[148:151], v[176:179], v[20:23], v[246:249]
	v_cvt_pk_bf16_f32 v170, v215, v214
	v_mfma_f32_16x16x32_bf16 v[140:143], v[176:179], v[44:47], v[140:143]
	s_waitcnt lgkmcnt(0)
	v_mfma_f32_16x16x32_bf16 v[132:135], v[210:213], v[20:23], v[128:131]
	v_cvt_pk_bf16_f32 v171, v218, v198
	v_mfma_f32_16x16x32_bf16 v[128:131], v[210:213], v[44:47], v[250:253]
	s_lshl_b32 s25, s5, 14
	s_add_i32 s25, s25, 0
	s_add_i32 s25, s25, 0x12000
	v_add_u32_e32 v235, s25, v222
	v_add_u32_e32 v236, s25, v223
	ds_read_b64_tr_b16 v[184:185], v236
	ds_read_b64_tr_b16 v[186:187], v236 offset:4096
	ds_read_b64_tr_b16 v[210:211], v236 offset:8192
	ds_read_b64_tr_b16 v[212:213], v236 offset:12288
	ds_read_b64_tr_b16 v[176:177], v235
	ds_read_b64_tr_b16 v[178:179], v235 offset:4096
	ds_read_b64_tr_b16 v[180:181], v235 offset:8192
	ds_read_b64_tr_b16 v[182:183], v235 offset:12288
	ds_read_b64_tr_b16 v[190:191], v236 offset:4608
	ds_read_b64_tr_b16 v[188:189], v236 offset:512
	ds_read_b64_tr_b16 v[240:241], v236 offset:12800
	ds_read_b64_tr_b16 v[238:239], v236 offset:8704
	s_waitcnt lgkmcnt(10)
	v_mfma_f32_16x16x32_bf16 v[112:115], v[184:187], v[136:139], v[112:115]
	v_mfma_f32_16x16x32_bf16 v[116:119], v[184:187], v[160:163], v[116:119]
	v_max_f32_e32 v184, v156, v157
	s_waitcnt lgkmcnt(8)
	v_mfma_f32_16x16x32_bf16 v[112:115], v[210:213], v[164:167], v[112:115]
	v_max3_f32 v184, v184, v158, v159
	v_max3_f32 v184, v184, v152, v153
	v_max3_f32 v184, v184, v154, v155
	v_mfma_f32_16x16x32_bf16 v[116:119], v[210:213], v[168:171], v[116:119]
	ds_read_b64_tr_b16 v[210:211], v235 offset:512
	ds_read_b64_tr_b16 v[212:213], v235 offset:4608
	ds_read_b64_tr_b16 v[242:243], v235 offset:8704
	ds_read_b64_tr_b16 v[244:245], v235 offset:12800
	s_waitcnt lgkmcnt(10)
	v_mfma_f32_16x16x32_bf16 v[104:107], v[176:179], v[136:139], v[104:107]
	v_mfma_f32_16x16x32_bf16 v[176:179], v[176:179], v[160:163], v[108:111]
	s_waitcnt lgkmcnt(8)
	v_mfma_f32_16x16x32_bf16 v[108:111], v[180:183], v[164:167], v[104:107]
	v_max3_f32 v252, v184, v148, v149
	v_max3_f32 v252, v252, v150, v151
	v_max3_f32 v252, v252, v132, v133
	v_max3_f32 v193, v252, v134, v135
	v_mfma_f32_16x16x32_bf16 v[104:107], v[180:183], v[168:171], v[176:179]
	ds_read_b64_tr_b16 v[184:185], v236 offset:1024
	ds_read_b64_tr_b16 v[186:187], v236 offset:5120
	s_nop 0
	ds_read_b64_tr_b16 v[176:177], v236 offset:9216
	ds_read_b64_tr_b16 v[178:179], v236 offset:13312
	s_waitcnt lgkmcnt(10)
	v_mfma_f32_16x16x32_bf16 v[96:99], v[188:191], v[136:139], v[96:99]
	v_max_f32_e32 v180, v144, v145
	s_waitcnt lgkmcnt(8)
	v_mfma_f32_16x16x32_bf16 v[96:99], v[238:241], v[164:167], v[96:99]
	v_max3_f32 v180, v180, v146, v147
	v_max3_f32 v180, v180, v172, v173
	v_max3_f32 v192, v180, v174, v175
	v_mfma_f32_16x16x32_bf16 v[100:103], v[188:191], v[160:163], v[100:103]
	v_mfma_f32_16x16x32_bf16 v[100:103], v[238:241], v[168:171], v[100:103]
	ds_read_b64_tr_b16 v[188:189], v235 offset:1024
	ds_read_b64_tr_b16 v[190:191], v235 offset:5120
	ds_read_b64_tr_b16 v[180:181], v235 offset:9216
	ds_read_b64_tr_b16 v[182:183], v235 offset:13312
	s_waitcnt lgkmcnt(10)
	v_mfma_f32_16x16x32_bf16 v[88:91], v[210:213], v[136:139], v[88:91]
	v_mfma_f32_16x16x32_bf16 v[210:213], v[210:213], v[160:163], v[92:95]
	s_waitcnt lgkmcnt(8)
	v_mfma_f32_16x16x32_bf16 v[92:95], v[242:245], v[164:167], v[88:91]
	v_max3_f32 v252, v192, v140, v141
	v_max3_f32 v252, v252, v142, v143
	v_max3_f32 v252, v252, v128, v129
	v_max3_f32 v237, v252, v130, v131
	v_mfma_f32_16x16x32_bf16 v[88:91], v[242:245], v[168:171], v[210:213]
	v_max_f32_e32 v192, v193, v237
	v_cmp_ge_f32_e32 vcc, s62, v192
	s_cmp_lg_u64 vcc, exec
	s_cselect_b64 s[36:37], -1, 0
	s_cmp_eq_u64 vcc, exec
	v_mov_b32_e32 v192, 1.0
	s_cbranch_scc1 .LBB0_973
	ds_bpermute_b32 v48, v220, v193
	v_max_f32_e32 v49, v193, v193
	v_max_f32_e32 v50, v237, v237
	s_waitcnt lgkmcnt(0)
	v_max_f32_e32 v48, v48, v48
	v_max_f32_e32 v48, v49, v48
	ds_bpermute_b32 v49, v221, v48
	s_waitcnt lgkmcnt(0)
	v_max3_f32 v48, v48, v49, 0
	ds_bpermute_b32 v49, v220, v237
	v_exp_f32_e64 v192, -v48
	v_sub_f32_e32 v156, v156, v48
	v_sub_f32_e32 v157, v157, v48
	v_sub_f32_e32 v158, v158, v48
	s_waitcnt lgkmcnt(0)
	v_max_f32_e32 v49, v49, v49
	v_max_f32_e32 v49, v50, v49
	ds_bpermute_b32 v50, v221, v49
	v_sub_f32_e32 v159, v159, v48
	v_sub_f32_e32 v152, v152, v48
	v_sub_f32_e32 v153, v153, v48
	v_sub_f32_e32 v154, v154, v48
	s_waitcnt lgkmcnt(0)
	v_max3_f32 v49, v49, v50, 0
	v_exp_f32_e64 v193, -v49
	v_pk_add_f32 v[202:203], v[202:203], v[48:49]
	v_sub_f32_e32 v155, v155, v48
	v_pk_add_f32 v[120:121], v[202:203], 0 neg_lo:[1,1] neg_hi:[1,1]
	v_xor_b32_e32 v124, 0x80000000, v203
	v_sub_f32_e32 v151, v151, v48
	v_sub_f32_e32 v150, v150, v48
	v_sub_f32_e32 v149, v149, v48
	v_sub_f32_e32 v148, v148, v48
	v_sub_f32_e32 v135, v135, v48
	v_sub_f32_e32 v134, v134, v48
	v_sub_f32_e32 v133, v133, v48
	v_sub_f32_e32 v132, v132, v48
	v_mov_b32_e32 v121, v120
	v_mov_b32_e32 v122, v120
	v_mov_b32_e32 v123, v120
	v_sub_f32_e32 v144, v144, v49
	v_sub_f32_e32 v145, v145, v49
	v_sub_f32_e32 v146, v146, v49
	v_sub_f32_e32 v147, v147, v49
	v_sub_f32_e32 v172, v172, v49
	v_sub_f32_e32 v173, v173, v49
	v_sub_f32_e32 v174, v174, v49
	v_sub_f32_e32 v175, v175, v49
	v_sub_f32_e32 v143, v143, v49
	v_sub_f32_e32 v142, v142, v49
	v_sub_f32_e32 v141, v141, v49
	v_sub_f32_e32 v140, v140, v49
	v_sub_f32_e32 v131, v131, v49
	v_sub_f32_e32 v130, v130, v49
	v_sub_f32_e32 v129, v129, v49
	v_sub_f32_e32 v128, v128, v49
	v_mov_b32_e32 v125, v124
	v_mov_b32_e32 v126, v124
	v_mov_b32_e32 v127, v124
	v_mov_b32_e32 v48, v120
	v_mov_b32_e32 v49, v120
	v_mov_b32_e32 v50, v120
	v_mov_b32_e32 v51, v120
	v_mov_b32_e32 v52, v124
	v_mov_b32_e32 v53, v124
	v_mov_b32_e32 v54, v124
	v_mov_b32_e32 v55, v124
	s_branch .LBB0_974
